# also balanced LDS-DMA staging (4+4 per segment, extra vmcnt(4)) in the layer-0 down-GEMM K-loop
# speedup vs baseline: 1.0065x; 1.0011x over previous
.LBB0_1190:
	s_add_u32 s14, s94, 0xf200000
	s_addc_u32 s15, s95, 0
	s_add_u32 s16, s94, 0x12000000
	s_mov_b64 s[18:19], 0x80
	s_addc_u32 s17, s95, 0
	s_bfe_u32 s43, s33, 0x20006
	s_add_i32 m0, s39, 0x18000
	v_lshl_add_u64 v[6:7], v[6:7], 0, s[18:19]
	s_lshl_b32 s44, s3, 6
	s_lshl_b32 s45, s43, 5
	s_waitcnt vmcnt(2)
	s_barrier
	global_load_lds_dwordx4 v[6:7], off
	v_lshl_add_u64 v[4:5], v[4:5], 0, s[18:19]
	s_add_i32 m0, s39, 0x1a000
	s_add_i32 s46, s39, 0x8000
	s_add_i32 s47, s39, 0xa000
	global_load_lds_dwordx4 v[4:5], off
	v_lshl_add_u64 v[0:1], v[0:1], 0, s[18:19]
	s_mov_b32 m0, s46
	s_add_u32 s20, s8, 0x200080
	global_load_lds_dwordx4 v[0:1], off
	v_lshl_add_u64 v[0:1], v[2:3], 0, s[18:19]
	s_mov_b32 m0, s47
	s_addc_u32 s21, s9, 0
	global_load_lds_dwordx4 v[0:1], off
	s_add_i32 m0, s39, 0x1c000
	v_lshl_add_u64 v[0:1], s[20:21], 0, v[188:189]
	global_load_lds_dwordx4 v[0:1], off
	v_lshl_add_u64 v[0:1], s[20:21], 0, v[184:185]
	s_add_i32 m0, s39, 0x1e000
	v_and_b32_e32 v229, 15, v9
	global_load_lds_dwordx4 v[0:1], off
	v_and_b32_e32 v0, 48, v9
	v_and_b32_e32 v1, 0xfffffc00, v11
	v_lshlrev_b32_e32 v3, 2, v9
	s_cmpk_lt_u32 s33, 0x100
	v_lshl_add_u32 v2, s3, 13, v1
	v_lshl_or_b32 v0, v229, 6, v0
	v_and_b32_e32 v3, 32, v3
	v_lshl_add_u32 v1, s43, 12, v1
	s_cselect_b64 s[22:23], -1, 0
	s_lshl_b32 s0, s0, 22
	v_bitop3_b32 v2, v0, v2, v3 bitop3:0xde
	v_bitop3_b32 v3, v0, v1, v3 bitop3:0xde
	s_lshl_b32 s1, s1, 22
	v_lshlrev_b32_e32 v0, 17, v13
	s_or_b32 s0, s2, s0
	v_and_b32_e32 v0, 0xfffc0000, v0
	s_add_u32 s0, s94, s0
	v_lshl_add_u32 v0, v14, 14, v0
	v_and_b32_e32 v1, 1, v13
	s_addc_u32 s2, s95, 0
	v_lshl_or_b32 v0, v1, 6, v0
	s_add_u32 s0, s0, s1
	v_lshl_add_u32 v0, v15, 1, v0
	v_mov_b32_e32 v1, v189
	s_addc_u32 s1, s2, 0
	v_lshl_add_u64 v[192:193], s[0:1], 0, v[0:1]
	v_lshlrev_b32_e32 v0, 17, v8
	v_and_b32_e32 v0, 0xfffc0000, v0
	v_lshl_add_u32 v0, v10, 14, v0
	v_and_b32_e32 v1, 1, v8
	v_lshl_or_b32 v0, v1, 6, v0
	s_waitcnt vmcnt(6)
	v_lshl_add_u32 v0, v12, 1, v0
	v_mov_b32_e32 v1, v189
	s_add_i32 s50, 0, 0x10000
	s_add_i32 s52, 0, 0x14000
	v_lshl_add_u64 v[194:195], s[0:1], 0, v[0:1]
	v_add_u32_e32 v230, s50, v3
	v_add_u32_e32 v231, s52, v3
	v_mbcnt_lo_u32_b32 v0, -1, 0
	s_add_i32 s50, s50, s37
	s_add_i32 s52, s52, s37
	s_add_i32 s54, 0, 0x18000
	s_add_i32 s55, 0, 0x1c000
	v_ashrrev_i32_e32 v228, 4, v9
	s_mov_b32 s21, 0
	v_add_u32_e32 v232, 0, v2
	s_mov_b64 s[24:25], 0x131fff80
	v_mbcnt_hi_u32_b32 v233, -1, v0
	s_add_i32 s48, s39, 0xc000
	s_add_i32 s49, s39, 0xe000
	s_add_i32 s51, s50, 0x2000
	s_add_i32 s53, s52, 0x2000
	v_add_u32_e32 v234, s54, v3
	v_add_u32_e32 v235, s55, v3
	s_mov_b32 s56, 0
	s_lshr_b32 s84, s88, 2
	s_mul_i32 s85, s84, 0x3000
	s_add_i32 s85, s85, s39
	s_mul_i32 s96, s84, 0x180000
	s_mov_b32 s97, 0
	s_sub_u32 s86, s24, 0x200000
	s_subb_u32 s87, s25, 0
	s_add_u32 s86, s86, s96
	s_addc_u32 s87, s87, 0
	s_barrier
	s_branch .LBB0_1193

.LBB0_1194:
	ds_read_b128 v[120:123], v230
	ds_read_b128 v[132:135], v230 offset:1024
	ds_read_b128 v[136:139], v230 offset:2048
	ds_read_b128 v[140:143], v230 offset:3072
	ds_read_b128 v[144:147], v231
	ds_read_b128 v[148:151], v231 offset:1024
	ds_read_b128 v[152:155], v231 offset:2048
	ds_read_b128 v[156:159], v231 offset:3072
	s_add_u32 s28, s0, s2
	s_addc_u32 s29, s1, s3
	s_cmpk_eq_i32 s2, 0x4000
	s_cselect_b32 s30, 0, s2
	s_cselect_b32 s31, 0, s3
	s_cselect_b32 s28, s57, s28
	s_cselect_b32 s29, s7, s29
	s_add_u32 s30, s10, s30
	s_addc_u32 s31, s11, s31
	s_add_u32 s98, s2, s86
	s_addc_u32 s99, s3, s87
	s_add_i32 m0, s85, 0x8000
	v_lshl_add_u64 v[204:205], v[192:193], 0, s[98:99]
	ds_read_b128 v[160:163], v232
	ds_read_b128 v[164:167], v232 offset:1024
	ds_read_b128 v[168:171], v232 offset:2048
	ds_read_b128 v[172:175], v232 offset:3072
	ds_read_b128 v[176:179], v232 offset:4096
	ds_read_b128 v[180:183], v232 offset:5120
	ds_read_b128 v[196:199], v232 offset:6144
	ds_read_b128 v[200:203], v232 offset:7168
	global_load_lds_dwordx4 v[204:205], off
	s_add_u32 s98, s98, 0x80000
	s_addc_u32 s99, s99, 0
	s_add_i32 m0, s85, 0x9000
	v_lshl_add_u64 v[204:205], v[192:193], 0, s[98:99]
	global_load_lds_dwordx4 v[204:205], off
	s_add_u32 s98, s98, 0x80000
	s_addc_u32 s99, s99, 0
	s_add_i32 m0, s85, 0xa000
	v_lshl_add_u64 v[204:205], v[192:193], 0, s[98:99]
	global_load_lds_dwordx4 v[204:205], off
	s_add_u32 s98, s98, 0x80000
	s_addc_u32 s99, s99, 0
	s_add_i32 m0, s85, 0xb000
	v_lshl_add_u64 v[204:205], v[192:193], 0, s[98:99]
	global_load_lds_dwordx4 v[204:205], off
	s_waitcnt vmcnt(8)
	s_waitcnt lgkmcnt(0)
	s_barrier
	s_setprio 1
	s_waitcnt lgkmcnt(0)
	v_mfma_f32_16x16x32_bf16 v[128:131], v[120:123], v[160:163], v[128:131]
	v_mfma_f32_16x16x32_bf16 v[124:127], v[136:139], v[160:163], v[124:127]
	v_mfma_f32_16x16x32_bf16 v[108:111], v[120:123], v[168:171], v[108:111]
	v_mfma_f32_16x16x32_bf16 v[104:107], v[136:139], v[168:171], v[104:107]
	v_mfma_f32_16x16x32_bf16 v[92:95], v[120:123], v[176:179], v[92:95]
	v_mfma_f32_16x16x32_bf16 v[88:91], v[136:139], v[176:179], v[88:91]
	v_mfma_f32_16x16x32_bf16 v[76:79], v[120:123], v[196:199], v[76:79]
	v_mfma_f32_16x16x32_bf16 v[72:75], v[136:139], v[196:199], v[72:75]
	v_mfma_f32_16x16x32_bf16 v[128:131], v[132:135], v[164:167], v[128:131]
	v_mfma_f32_16x16x32_bf16 v[124:127], v[140:143], v[164:167], v[124:127]
	v_mfma_f32_16x16x32_bf16 v[108:111], v[132:135], v[172:175], v[108:111]
	v_mfma_f32_16x16x32_bf16 v[104:107], v[140:143], v[172:175], v[104:107]
	v_mfma_f32_16x16x32_bf16 v[92:95], v[132:135], v[180:183], v[92:95]
	v_mfma_f32_16x16x32_bf16 v[88:91], v[140:143], v[180:183], v[88:91]
	v_mfma_f32_16x16x32_bf16 v[76:79], v[132:135], v[200:203], v[76:79]
	v_mfma_f32_16x16x32_bf16 v[72:75], v[140:143], v[200:203], v[72:75]
	s_setprio 0
	s_setprio 1
	v_mfma_f32_16x16x32_bf16 v[116:119], v[144:147], v[160:163], v[116:119]
	v_mfma_f32_16x16x32_bf16 v[112:115], v[152:155], v[160:163], v[112:115]
	v_mfma_f32_16x16x32_bf16 v[100:103], v[144:147], v[168:171], v[100:103]
	v_mfma_f32_16x16x32_bf16 v[96:99], v[152:155], v[168:171], v[96:99]
	v_mfma_f32_16x16x32_bf16 v[84:87], v[144:147], v[176:179], v[84:87]
	v_mfma_f32_16x16x32_bf16 v[80:83], v[152:155], v[176:179], v[80:83]
	v_mfma_f32_16x16x32_bf16 v[68:71], v[144:147], v[196:199], v[68:71]
	v_mfma_f32_16x16x32_bf16 v[64:67], v[152:155], v[196:199], v[64:67]
	v_mfma_f32_16x16x32_bf16 v[116:119], v[148:151], v[164:167], v[116:119]
	v_mfma_f32_16x16x32_bf16 v[112:115], v[156:159], v[164:167], v[112:115]
	v_mfma_f32_16x16x32_bf16 v[100:103], v[148:151], v[172:175], v[100:103]
	v_mfma_f32_16x16x32_bf16 v[96:99], v[156:159], v[172:175], v[96:99]
	v_mfma_f32_16x16x32_bf16 v[84:87], v[148:151], v[180:183], v[84:87]
	v_mfma_f32_16x16x32_bf16 v[80:83], v[156:159], v[180:183], v[80:83]
	v_mfma_f32_16x16x32_bf16 v[68:71], v[148:151], v[200:203], v[68:71]
	v_mfma_f32_16x16x32_bf16 v[64:67], v[156:159], v[200:203], v[64:67]
	s_setprio 0
	s_barrier
	s_mov_b32 m0, s50
	v_lshl_add_u64 v[204:205], s[28:29], 0, v[188:189]
	s_add_u32 s60, s28, 0x200000
	ds_read_b128 v[160:163], v232 offset:16384
	ds_read_b128 v[164:167], v232 offset:17408
	ds_read_b128 v[168:171], v232 offset:18432
	ds_read_b128 v[172:175], v232 offset:19456
	ds_read_b128 v[176:179], v232 offset:20480
	ds_read_b128 v[180:183], v232 offset:21504
	ds_read_b128 v[196:199], v232 offset:22528
	ds_read_b128 v[200:203], v232 offset:23552
	global_load_lds_dwordx4 v[204:205], off
	v_lshl_add_u64 v[206:207], s[28:29], 0, v[184:185]
	s_mov_b32 m0, s51
	s_addc_u32 s61, s29, 0
	global_load_lds_dwordx4 v[206:207], off
	v_lshl_add_u64 v[208:209], s[60:61], 0, v[188:189]
	s_mov_b32 m0, s52
	global_load_lds_dwordx4 v[208:209], off
	v_lshl_add_u64 v[208:209], s[60:61], 0, v[184:185]
	s_mov_b32 m0, s53
	s_nop 0
	global_load_lds_dwordx4 v[208:209], off
	s_waitcnt vmcnt(8)
	s_waitcnt lgkmcnt(0)
	s_barrier
	s_setprio 1
	s_waitcnt lgkmcnt(0)
	v_mfma_f32_16x16x32_bf16 v[60:63], v[120:123], v[160:163], v[60:63]
	v_mfma_f32_16x16x32_bf16 v[56:59], v[136:139], v[160:163], v[56:59]
	v_mfma_f32_16x16x32_bf16 v[44:47], v[120:123], v[168:171], v[44:47]
	v_mfma_f32_16x16x32_bf16 v[40:43], v[136:139], v[168:171], v[40:43]
	v_mfma_f32_16x16x32_bf16 v[28:31], v[120:123], v[176:179], v[28:31]
	v_mfma_f32_16x16x32_bf16 v[24:27], v[136:139], v[176:179], v[24:27]
	v_mfma_f32_16x16x32_bf16 v[12:15], v[120:123], v[196:199], v[12:15]
	v_mfma_f32_16x16x32_bf16 v[8:11], v[136:139], v[196:199], v[8:11]
	v_mfma_f32_16x16x32_bf16 v[60:63], v[132:135], v[164:167], v[60:63]
	v_mfma_f32_16x16x32_bf16 v[56:59], v[140:143], v[164:167], v[56:59]
	v_mfma_f32_16x16x32_bf16 v[44:47], v[132:135], v[172:175], v[44:47]
	v_mfma_f32_16x16x32_bf16 v[40:43], v[140:143], v[172:175], v[40:43]
	v_mfma_f32_16x16x32_bf16 v[28:31], v[132:135], v[180:183], v[28:31]
	v_mfma_f32_16x16x32_bf16 v[24:27], v[140:143], v[180:183], v[24:27]
	v_mfma_f32_16x16x32_bf16 v[12:15], v[132:135], v[200:203], v[12:15]
	v_mfma_f32_16x16x32_bf16 v[8:11], v[140:143], v[200:203], v[8:11]
	s_setprio 0
	s_setprio 1
	v_mfma_f32_16x16x32_bf16 v[52:55], v[144:147], v[160:163], v[52:55]
	v_mfma_f32_16x16x32_bf16 v[48:51], v[152:155], v[160:163], v[48:51]
	v_mfma_f32_16x16x32_bf16 v[36:39], v[144:147], v[168:171], v[36:39]
	v_mfma_f32_16x16x32_bf16 v[32:35], v[152:155], v[168:171], v[32:35]
	v_mfma_f32_16x16x32_bf16 v[20:23], v[144:147], v[176:179], v[20:23]
	v_mfma_f32_16x16x32_bf16 v[16:19], v[152:155], v[176:179], v[16:19]
	v_mfma_f32_16x16x32_bf16 v[4:7], v[144:147], v[196:199], v[4:7]
	v_mfma_f32_16x16x32_bf16 v[0:3], v[152:155], v[196:199], v[0:3]
	v_mfma_f32_16x16x32_bf16 v[52:55], v[148:151], v[164:167], v[52:55]
	v_mfma_f32_16x16x32_bf16 v[48:51], v[156:159], v[164:167], v[48:51]
	v_mfma_f32_16x16x32_bf16 v[36:39], v[148:151], v[172:175], v[36:39]
	v_mfma_f32_16x16x32_bf16 v[32:35], v[156:159], v[172:175], v[32:35]
	v_mfma_f32_16x16x32_bf16 v[20:23], v[148:151], v[180:183], v[20:23]
	v_mfma_f32_16x16x32_bf16 v[16:19], v[156:159], v[180:183], v[16:19]
	v_mfma_f32_16x16x32_bf16 v[4:7], v[148:151], v[200:203], v[4:7]
	v_mfma_f32_16x16x32_bf16 v[0:3], v[156:159], v[200:203], v[0:3]
	s_setprio 0
	s_waitcnt vmcnt(4)
	s_barrier
	ds_read_b128 v[120:123], v234
	ds_read_b128 v[132:135], v234 offset:1024
	ds_read_b128 v[136:139], v234 offset:2048
	ds_read_b128 v[140:143], v234 offset:3072
	ds_read_b128 v[144:147], v235
	ds_read_b128 v[148:151], v235 offset:1024
	ds_read_b128 v[152:155], v235 offset:2048
	ds_read_b128 v[156:159], v235 offset:3072
	s_add_u32 s98, s30, s96
	s_addc_u32 s99, s31, s97
	s_add_i32 m0, s85, 0
	v_lshl_add_u64 v[212:213], s[98:99], 0, v[190:191]
	ds_read_b128 v[160:163], v232 offset:32768
	ds_read_b128 v[164:167], v232 offset:33792
	ds_read_b128 v[168:171], v232 offset:34816
	ds_read_b128 v[172:175], v232 offset:35840
	ds_read_b128 v[176:179], v232 offset:36864
	ds_read_b128 v[180:183], v232 offset:37888
	ds_read_b128 v[196:199], v232 offset:38912
	ds_read_b128 v[200:203], v232 offset:39936
	global_load_lds_dwordx4 v[212:213], off
	s_add_u32 s98, s98, 0x80000
	s_addc_u32 s99, s99, 0
	s_add_i32 m0, s85, 0x1000
	v_lshl_add_u64 v[212:213], s[98:99], 0, v[190:191]
	global_load_lds_dwordx4 v[212:213], off
	s_add_u32 s98, s98, 0x80000
	s_addc_u32 s99, s99, 0
	s_add_i32 m0, s85, 0x2000
	v_lshl_add_u64 v[212:213], s[98:99], 0, v[190:191]
	global_load_lds_dwordx4 v[212:213], off
	s_add_u32 s98, s98, 0x80000
	s_addc_u32 s99, s99, 0
	s_add_i32 m0, s85, 0x3000
	v_lshl_add_u64 v[212:213], s[98:99], 0, v[190:191]
	global_load_lds_dwordx4 v[212:213], off
	s_waitcnt vmcnt(8)
	s_waitcnt lgkmcnt(0)
	s_barrier
	s_setprio 1
	s_waitcnt lgkmcnt(0)
	v_mfma_f32_16x16x32_bf16 v[128:131], v[120:123], v[160:163], v[128:131]
	v_mfma_f32_16x16x32_bf16 v[124:127], v[136:139], v[160:163], v[124:127]
	v_mfma_f32_16x16x32_bf16 v[108:111], v[120:123], v[168:171], v[108:111]
	v_mfma_f32_16x16x32_bf16 v[104:107], v[136:139], v[168:171], v[104:107]
	v_mfma_f32_16x16x32_bf16 v[92:95], v[120:123], v[176:179], v[92:95]
	v_mfma_f32_16x16x32_bf16 v[88:91], v[136:139], v[176:179], v[88:91]
	v_mfma_f32_16x16x32_bf16 v[76:79], v[120:123], v[196:199], v[76:79]
	v_mfma_f32_16x16x32_bf16 v[72:75], v[136:139], v[196:199], v[72:75]
	v_mfma_f32_16x16x32_bf16 v[128:131], v[132:135], v[164:167], v[128:131]
	v_mfma_f32_16x16x32_bf16 v[124:127], v[140:143], v[164:167], v[124:127]
	v_mfma_f32_16x16x32_bf16 v[108:111], v[132:135], v[172:175], v[108:111]
	v_mfma_f32_16x16x32_bf16 v[104:107], v[140:143], v[172:175], v[104:107]
	v_mfma_f32_16x16x32_bf16 v[92:95], v[132:135], v[180:183], v[92:95]
	v_mfma_f32_16x16x32_bf16 v[88:91], v[140:143], v[180:183], v[88:91]
	v_mfma_f32_16x16x32_bf16 v[76:79], v[132:135], v[200:203], v[76:79]
	v_mfma_f32_16x16x32_bf16 v[72:75], v[140:143], v[200:203], v[72:75]
	s_setprio 0
	s_setprio 1
	v_mfma_f32_16x16x32_bf16 v[116:119], v[144:147], v[160:163], v[116:119]
	v_mfma_f32_16x16x32_bf16 v[112:115], v[152:155], v[160:163], v[112:115]
	v_mfma_f32_16x16x32_bf16 v[100:103], v[144:147], v[168:171], v[100:103]
	v_mfma_f32_16x16x32_bf16 v[96:99], v[152:155], v[168:171], v[96:99]
	v_mfma_f32_16x16x32_bf16 v[84:87], v[144:147], v[176:179], v[84:87]
	v_mfma_f32_16x16x32_bf16 v[80:83], v[152:155], v[176:179], v[80:83]
	v_mfma_f32_16x16x32_bf16 v[68:71], v[144:147], v[196:199], v[68:71]
	v_mfma_f32_16x16x32_bf16 v[64:67], v[152:155], v[196:199], v[64:67]
	v_mfma_f32_16x16x32_bf16 v[116:119], v[148:151], v[164:167], v[116:119]
	v_mfma_f32_16x16x32_bf16 v[112:115], v[156:159], v[164:167], v[112:115]
	v_mfma_f32_16x16x32_bf16 v[100:103], v[148:151], v[172:175], v[100:103]
	v_mfma_f32_16x16x32_bf16 v[96:99], v[156:159], v[172:175], v[96:99]
	v_mfma_f32_16x16x32_bf16 v[84:87], v[148:151], v[180:183], v[84:87]
	v_mfma_f32_16x16x32_bf16 v[80:83], v[156:159], v[180:183], v[80:83]
	v_mfma_f32_16x16x32_bf16 v[68:71], v[148:151], v[200:203], v[68:71]
	v_mfma_f32_16x16x32_bf16 v[64:67], v[156:159], v[200:203], v[64:67]
	s_setprio 0
	s_barrier
	s_add_i32 s30, s54, s37
	v_lshl_add_u64 v[204:205], v[204:205], 0, s[18:19]
	s_mov_b32 m0, s30
	ds_read_b128 v[160:163], v232 offset:49152
	ds_read_b128 v[164:167], v232 offset:50176
	ds_read_b128 v[168:171], v232 offset:51200
	ds_read_b128 v[172:175], v232 offset:52224
	ds_read_b128 v[176:179], v232 offset:53248
	ds_read_b128 v[180:183], v232 offset:54272
	ds_read_b128 v[196:199], v232 offset:55296
	ds_read_b128 v[200:203], v232 offset:56320
	global_load_lds_dwordx4 v[204:205], off
	s_add_i32 m0, s30, 0x2000
	s_add_u32 s28, s28, 0x200080
	v_lshl_add_u64 v[204:205], v[206:207], 0, s[18:19]
	s_addc_u32 s29, s29, 0
	s_add_i32 s30, s55, s37
	global_load_lds_dwordx4 v[204:205], off
	v_lshl_add_u64 v[204:205], s[28:29], 0, v[188:189]
	s_mov_b32 m0, s30
	s_nop 0
	global_load_lds_dwordx4 v[204:205], off
	v_lshl_add_u64 v[204:205], s[28:29], 0, v[184:185]
	s_add_i32 m0, s30, 0x2000
	s_nop 0
	global_load_lds_dwordx4 v[204:205], off
	s_waitcnt vmcnt(8)
	s_waitcnt lgkmcnt(0)
	s_barrier
	s_setprio 1
	s_waitcnt lgkmcnt(0)
	v_mfma_f32_16x16x32_bf16 v[60:63], v[120:123], v[160:163], v[60:63]
	v_mfma_f32_16x16x32_bf16 v[56:59], v[136:139], v[160:163], v[56:59]
	v_mfma_f32_16x16x32_bf16 v[44:47], v[120:123], v[168:171], v[44:47]
	v_mfma_f32_16x16x32_bf16 v[40:43], v[136:139], v[168:171], v[40:43]
	v_mfma_f32_16x16x32_bf16 v[28:31], v[120:123], v[176:179], v[28:31]
	v_mfma_f32_16x16x32_bf16 v[24:27], v[136:139], v[176:179], v[24:27]
	v_mfma_f32_16x16x32_bf16 v[12:15], v[120:123], v[196:199], v[12:15]
	v_mfma_f32_16x16x32_bf16 v[8:11], v[136:139], v[196:199], v[8:11]
	v_mfma_f32_16x16x32_bf16 v[60:63], v[132:135], v[164:167], v[60:63]
	v_mfma_f32_16x16x32_bf16 v[56:59], v[140:143], v[164:167], v[56:59]
	v_mfma_f32_16x16x32_bf16 v[44:47], v[132:135], v[172:175], v[44:47]
	v_mfma_f32_16x16x32_bf16 v[40:43], v[140:143], v[172:175], v[40:43]
	v_mfma_f32_16x16x32_bf16 v[28:31], v[132:135], v[180:183], v[28:31]
	v_mfma_f32_16x16x32_bf16 v[24:27], v[140:143], v[180:183], v[24:27]
	v_mfma_f32_16x16x32_bf16 v[12:15], v[132:135], v[200:203], v[12:15]
	v_mfma_f32_16x16x32_bf16 v[8:11], v[140:143], v[200:203], v[8:11]
	s_setprio 0
	s_setprio 1
	v_mfma_f32_16x16x32_bf16 v[52:55], v[144:147], v[160:163], v[52:55]
	v_mfma_f32_16x16x32_bf16 v[48:51], v[152:155], v[160:163], v[48:51]
	v_mfma_f32_16x16x32_bf16 v[36:39], v[144:147], v[168:171], v[36:39]
	v_mfma_f32_16x16x32_bf16 v[32:35], v[152:155], v[168:171], v[32:35]
	v_mfma_f32_16x16x32_bf16 v[20:23], v[144:147], v[176:179], v[20:23]
	v_mfma_f32_16x16x32_bf16 v[16:19], v[152:155], v[176:179], v[16:19]
	v_mfma_f32_16x16x32_bf16 v[4:7], v[144:147], v[196:199], v[4:7]
	v_mfma_f32_16x16x32_bf16 v[0:3], v[152:155], v[196:199], v[0:3]
	v_mfma_f32_16x16x32_bf16 v[52:55], v[148:151], v[164:167], v[52:55]
	v_mfma_f32_16x16x32_bf16 v[48:51], v[156:159], v[164:167], v[48:51]
	v_mfma_f32_16x16x32_bf16 v[36:39], v[148:151], v[172:175], v[36:39]
	v_mfma_f32_16x16x32_bf16 v[32:35], v[156:159], v[172:175], v[32:35]
	v_mfma_f32_16x16x32_bf16 v[20:23], v[148:151], v[180:183], v[20:23]
	v_mfma_f32_16x16x32_bf16 v[16:19], v[156:159], v[180:183], v[16:19]
	v_mfma_f32_16x16x32_bf16 v[4:7], v[148:151], v[200:203], v[4:7]
	v_mfma_f32_16x16x32_bf16 v[0:3], v[156:159], v[200:203], v[0:3]
	s_setprio 0
	s_waitcnt vmcnt(4)
	s_barrier
	s_add_i32 s58, s58, 2
	s_add_u32 s2, s2, 0x100
	s_addc_u32 s3, s3, 0
	s_cmpk_gt_u32 s58, 0x7d
	s_cbranch_scc0 .LBB0_1194
	s_and_b64 vcc, exec, s[22:23]
	s_cbranch_vccz .LBB0_1197
	s_barrier
